# diff attention: in-loop T5 bias-table adds batched (16 ds_read2 in flight instead of serialized)
# speedup vs baseline: 1.0026x; 1.0026x over previous
; #define LAS __attribute__((address_space(3)))
; #define SBAR() __builtin_amdgcn_sched_barrier(0)
; #define SBAR() __builtin_amdgcn_sched_barrier(0)
; template <bool BIAS>
; __device__ __forceinline__ void bias_add(f32x16& p0, f32x16& p1, int bmode, const LAS float* tab, int idx0) {
;     if constexpr (BIAS) {
;         if (bmode == 2) {
; #pragma unroll
;             for (int r = 0; r < 16; ++r) { const int o = (r & 3) + 8 * (r >> 2); p0[r] += tab[idx0 + o]; p1[r] += tab[idx0 + 32 + o]; if ((r & 3) == 3) { asm volatile("" : "+v"(p0), "+v"(p1)); SBAR(); } }
;         }
.LBB0_518:
	ds_read2_b32 v[94:95], v218 offset1:1
	ds_read2_b32 v[96:97], v218 offset0:32 offset1:33
	ds_read2_b32 v[106:107], v218 offset0:2 offset1:3
	ds_read2_b32 v[108:109], v218 offset0:34 offset1:35
	ds_read2_b32 v[110:111], v218 offset0:8 offset1:9
	ds_read2_b32 v[112:113], v218 offset0:40 offset1:41
	ds_read2_b32 v[220:221], v218 offset0:10 offset1:11
	ds_read2_b32 v[222:223], v218 offset0:42 offset1:43
	s_waitcnt lgkmcnt(7)
	v_pk_add_f32 v[130:131], v[130:131], v[94:95]
	ds_read2_b32 v[224:225], v218 offset0:16 offset1:17
	s_waitcnt lgkmcnt(7)
	v_pk_add_f32 v[114:115], v[114:115], v[96:97]
	ds_read2_b32 v[226:227], v218 offset0:48 offset1:49
	s_waitcnt lgkmcnt(7)
	v_pk_add_f32 v[132:133], v[132:133], v[106:107]
	ds_read2_b32 v[228:229], v218 offset0:18 offset1:19
	s_waitcnt lgkmcnt(7)
	v_pk_add_f32 v[116:117], v[116:117], v[108:109]
	ds_read2_b32 v[244:245], v218 offset0:50 offset1:51
	s_waitcnt lgkmcnt(7)
	v_pk_add_f32 v[134:135], v[110:111], v[134:135]
	ds_read2_b32 v[246:247], v218 offset0:24 offset1:25
	s_waitcnt lgkmcnt(7)
	v_pk_add_f32 v[118:119], v[118:119], v[112:113]
	ds_read2_b32 v[248:249], v218 offset0:56 offset1:57
	s_waitcnt lgkmcnt(7)
	v_pk_add_f32 v[136:137], v[136:137], v[220:221]
	ds_read2_b32 v[250:251], v218 offset0:26 offset1:27
	s_waitcnt lgkmcnt(7)
	v_pk_add_f32 v[120:121], v[120:121], v[222:223]
	ds_read2_b32 v[252:253], v218 offset0:58 offset1:59
	s_waitcnt lgkmcnt(7)
	v_pk_add_f32 v[138:139], v[224:225], v[138:139]
	s_waitcnt lgkmcnt(6)
	v_pk_add_f32 v[122:123], v[122:123], v[226:227]
	s_waitcnt lgkmcnt(5)
	v_pk_add_f32 v[140:141], v[140:141], v[228:229]
	s_waitcnt lgkmcnt(4)
	v_pk_add_f32 v[124:125], v[124:125], v[244:245]
	s_waitcnt lgkmcnt(3)
	v_pk_add_f32 v[142:143], v[246:247], v[142:143]
	s_waitcnt lgkmcnt(2)
	v_pk_add_f32 v[126:127], v[126:127], v[248:249]
	s_waitcnt lgkmcnt(1)
	v_pk_add_f32 v[144:145], v[144:145], v[250:251]
	s_waitcnt lgkmcnt(0)
	v_pk_add_f32 v[128:129], v[128:129], v[252:253]
	s_nop 0

.LBB0_521:
	s_cmp_lg_u32 s14, 4
	s_cselect_b32 s9, s9, 0
	s_lshl_b32 s12, s14, 14
	s_cmpk_gt_u32 s66, 0x15c
	v_add_u32_e32 v222, s12, v204
	v_lshl_add_u32 v228, s9, 13, v205
	s_waitcnt lgkmcnt(1)
	v_mfma_f32_32x32x16_bf16 v[98:113], v[82:85], v[158:161], v[34:49]
	ds_read_b128 v[224:227], v228 offset:2048
	v_cvt_pk_bf16_f32 v162, v130, v131
	v_cvt_pk_bf16_f32 v163, v132, v133
	s_nop 0
	ds_read_b128 v[130:133], v228 offset:2560
	v_cvt_pk_bf16_f32 v164, v134, v135
	v_cvt_pk_bf16_f32 v165, v136, v137
	s_waitcnt lgkmcnt(2)
	v_mfma_f32_32x32x16_bf16 v[82:97], v[166:169], v[158:161], v[34:49]
	s_waitcnt lgkmcnt(1)
	v_mfma_f32_32x32x16_bf16 v[98:113], v[224:227], v[154:157], v[98:113]
	ds_read_b128 v[166:169], v228 offset:4096
	v_mfma_f32_16x16x32_bf16 v[240:243], v[162:165], v[236:239], v[240:243]
	v_cvt_pk_bf16_f32 v134, v138, v139
	v_cvt_pk_bf16_f32 v135, v140, v141
	s_waitcnt lgkmcnt(1)
	v_mfma_f32_32x32x16_bf16 v[82:97], v[130:133], v[154:157], v[82:97]
	ds_read_b128 v[138:141], v228 offset:4608
	v_cvt_pk_bf16_f32 v136, v142, v143
	v_cvt_pk_bf16_f32 v137, v144, v145
	s_waitcnt lgkmcnt(1)
	v_mfma_f32_32x32x16_bf16 v[98:113], v[166:169], v[150:153], v[98:113]
	ds_read_b128 v[142:145], v228 offset:6144
	v_mfma_f32_16x16x32_bf16 v[240:243], v[134:137], v[236:239], v[240:243]
	v_cvt_pk_bf16_f32 v130, v114, v115
	v_cvt_pk_bf16_f32 v131, v116, v117
	s_waitcnt lgkmcnt(1)
	v_mfma_f32_32x32x16_bf16 v[82:97], v[138:141], v[150:153], v[82:97]
	ds_read_b128 v[166:169], v228 offset:6656
	v_cvt_pk_bf16_f32 v132, v118, v119
	v_cvt_pk_bf16_f32 v133, v120, v121
	s_waitcnt lgkmcnt(1)
	v_mfma_f32_32x32x16_bf16 v[98:113], v[142:145], v[146:149], v[98:113]
	v_cvt_pk_bf16_f32 v114, v122, v123
	v_mfma_f32_16x16x32_bf16 v[240:243], v[130:133], v[236:239], v[240:243]
	v_cvt_pk_bf16_f32 v115, v124, v125
	ds_read_b64_tr_b16 v[122:123], v222
	ds_read_b64_tr_b16 v[124:125], v222 offset:2048
	s_waitcnt lgkmcnt(2)
	v_mfma_f32_32x32x16_bf16 v[82:97], v[166:169], v[146:149], v[82:97]
	v_cvt_pk_bf16_f32 v116, v126, v127
	v_cvt_pk_bf16_f32 v117, v128, v129
	ds_read_b64_tr_b16 v[118:119], v222 offset:512
	ds_read_b64_tr_b16 v[120:121], v222 offset:2560
	s_cbranch_scc1 .LBB0_512
	ds_read2_b32 v[126:127], v218 offset0:64 offset1:65
	ds_read2_b32 v[128:129], v218 offset0:96 offset1:97
	ds_read2_b32 v[138:139], v218 offset0:66 offset1:67
	ds_read2_b32 v[140:141], v218 offset0:98 offset1:99
	ds_read2_b32 v[142:143], v218 offset0:72 offset1:73
	ds_read2_b32 v[144:145], v218 offset0:104 offset1:105
	ds_read2_b32 v[166:167], v218 offset0:74 offset1:75
	ds_read2_b32 v[168:169], v218 offset0:106 offset1:107
	s_waitcnt lgkmcnt(7)
	v_pk_add_f32 v[98:99], v[98:99], v[126:127]
	ds_read2_b32 v[224:225], v218 offset0:80 offset1:81
	s_waitcnt lgkmcnt(7)
	v_pk_add_f32 v[82:83], v[82:83], v[128:129]
	ds_read2_b32 v[226:227], v218 offset0:112 offset1:113
	s_waitcnt lgkmcnt(7)
	v_pk_add_f32 v[100:101], v[100:101], v[138:139]
	ds_read2_b32 v[228:229], v218 offset0:82 offset1:83
	s_waitcnt lgkmcnt(7)
	v_pk_add_f32 v[84:85], v[84:85], v[140:141]
	ds_read2_b32 v[244:245], v218 offset0:114 offset1:115
	s_waitcnt lgkmcnt(7)
	v_pk_add_f32 v[102:103], v[142:143], v[102:103]
	ds_read2_b32 v[246:247], v218 offset0:88 offset1:89
	s_waitcnt lgkmcnt(7)
	v_pk_add_f32 v[86:87], v[86:87], v[144:145]
	ds_read2_b32 v[248:249], v218 offset0:120 offset1:121
	s_waitcnt lgkmcnt(7)
	v_pk_add_f32 v[104:105], v[104:105], v[166:167]
	ds_read2_b32 v[250:251], v218 offset0:90 offset1:91
	s_waitcnt lgkmcnt(7)
	v_pk_add_f32 v[88:89], v[88:89], v[168:169]
	ds_read2_b32 v[252:253], v218 offset0:122 offset1:123
	s_waitcnt lgkmcnt(7)
	v_pk_add_f32 v[106:107], v[224:225], v[106:107]
	s_waitcnt lgkmcnt(6)
	v_pk_add_f32 v[90:91], v[90:91], v[226:227]
	s_waitcnt lgkmcnt(5)
	v_pk_add_f32 v[108:109], v[108:109], v[228:229]
	s_waitcnt lgkmcnt(4)
	v_pk_add_f32 v[92:93], v[92:93], v[244:245]
	s_waitcnt lgkmcnt(3)
	v_pk_add_f32 v[110:111], v[246:247], v[110:111]
	s_waitcnt lgkmcnt(2)
	v_pk_add_f32 v[94:95], v[94:95], v[248:249]
	s_waitcnt lgkmcnt(1)
	v_pk_add_f32 v[112:113], v[112:113], v[250:251]
	s_waitcnt lgkmcnt(0)
	v_pk_add_f32 v[96:97], v[96:97], v[252:253]
	s_nop 0
	s_branch .LBB0_512
